# attention loop: counted lgkmcnt(2)/(1) waits before each MFMA instead of lgkmcnt(0)
# speedup vs baseline: 1.0196x; 1.0196x over previous
; #define AT_ADV() do { kg[0] += 64 * 1024; kg[1] += 64 * 1024; vg[0] += 64; vg[1] += 64; } while (0)
; __device__ __forceinline__ void attn_unit(unsigned char* ws, const float* sub_g, LAS unsigned char* lds, int h, int qb, float negM, float lam) {
;     ...
;     for (int t = 1; t < AT_NT; ++t) {
;         AT_DMA(bW);
;         if (t + 2 < AT_NT) AT_ADV();
;         SB();
;     ...
;         f32x16 s0, s1;
;         bf16x8 F0 = FLOAD(0), F1 = FLOAD(1), F2;
;         SB();
;         F2 = FLOAD(2); s0 = __builtin_amdgcn_mfma_f32_32x32x16_bf16(F0, qf[0], negm, 0, 0, 0); ADD4(pa, 0); pw[0][0] = cvtpk(pa[0], pa[1]); SB();
;         F0 = FLOAD(3); s1 = __builtin_amdgcn_mfma_f32_32x32x16_bf16(F1, qf[0], negm, 0, 0, 0); ADD4(pa, 4); pw[0][1] = cvtpk(pa[2], pa[3]); SB();
;         F1 = FLOAD(4); s0 = __builtin_amdgcn_mfma_f32_32x32x16_bf16(F2, qf[1], s0, 0, 0, 0); ADD4(pa, 8); pw[0][2] = cvtpk(pa[4], pa[5]); SB();
;         F2 = FLOAD(5); s1 = __builtin_amdgcn_mfma_f32_32x32x16_bf16(F0, qf[1], s1, 0, 0, 0); ADD4(pa, 12); pw[0][3] = cvtpk(pa[6], pa[7]); SB();
;         F0 = FLOAD(6); s0 = __builtin_amdgcn_mfma_f32_32x32x16_bf16(F1, qf[2], s0, 0, 0, 0); ADD4(pb, 0); pw[1][0] = cvtpk(pa[8], pa[9]); SB();
;         F1 = FLOAD(7); s1 = __builtin_amdgcn_mfma_f32_32x32x16_bf16(F2, qf[2], s1, 0, 0, 0); ADD4(pb, 4); pw[1][1] = cvtpk(pa[10], pa[11]); SB();
;         F2 = FLOAD(8); s0 = __builtin_amdgcn_mfma_f32_32x32x16_bf16(F0, qf[3], s0, 0, 0, 0); ADD4(pb, 8); pw[1][2] = cvtpk(pa[12], pa[13]); SB();
;         F0 = FLOAD(9); s1 = __builtin_amdgcn_mfma_f32_32x32x16_bf16(F1, qf[3], s1, 0, 0, 0); ADD4(pb, 12); pw[1][3] = cvtpk(pa[14], pa[15]); SB();
;         F1 = FLOAD(10); o[0] = __builtin_amdgcn_mfma_f32_32x32x16_bf16(F2, __builtin_bit_cast(bf16x8, pw[0]), o[0], 0, 0, 0); pw[2][0] = cvtpk(pb[0], pb[1]); EXP2(s0, pa, 0); SB();
;         F2 = FLOAD(11); o[1] = __builtin_amdgcn_mfma_f32_32x32x16_bf16(F0, __builtin_bit_cast(bf16x8, pw[0]), o[1], 0, 0, 0); pw[2][1] = cvtpk(pb[2], pb[3]); EXP2(s0, pa, 2); SB();
;         F0 = FLOAD(12); o[2] = __builtin_amdgcn_mfma_f32_32x32x16_bf16(F1, __builtin_bit_cast(bf16x8, pw[0]), o[2], 0, 0, 0); pw[2][2] = cvtpk(pb[4], pb[5]); EXP2(s0, pa, 4); SB();
;         F1 = FLOAD(13); o[3] = __builtin_amdgcn_mfma_f32_32x32x16_bf16(F2, __builtin_bit_cast(bf16x8, pw[0]), o[3], 0, 0, 0); pw[2][3] = cvtpk(pb[6], pb[7]); EXP2(s0, pa, 6); SB();
.LBB0_831:
	v_add_u32_e32 v84, s30, v198
	ds_read_b128 v[80:83], v84
	ds_read_b128 v[224:227], v84 offset:8192
	s_add_i32 s34, s30, 0
	v_add_u32_e32 v84, s34, v200
	ds_read_b128 v[228:231], v84
	v_add_f32_e32 v85, v216, v217
	v_add_f32_e32 v86, v199, v219
	s_waitcnt lgkmcnt(2)
	v_mfma_f32_32x32x16_bf16 v[96:111], v[80:83], v[112:115], v[0:15]
	v_add_f32_e32 v85, v85, v218
	v_add_f32_e32 v80, v86, v222
	v_cvt_pk_bf16_f32 v232, v217, v219
	ds_read_b128 v[236:239], v84 offset:8192
	v_add_f32_e32 v81, v85, v211
	v_add_f32_e32 v80, v80, v215
	v_cvt_pk_bf16_f32 v233, v218, v222
	v_add_f32_e32 v199, v81, v209
	v_add_f32_e32 v223, v80, v213
	s_waitcnt lgkmcnt(2)
	v_mfma_f32_32x32x16_bf16 v[80:95], v[224:227], v[112:115], v[0:15]
	v_add_u32_e32 v222, s34, v201
	ds_read_b128 v[216:219], v222
	v_add_f32_e32 v199, v199, v210
	v_add_f32_e32 v223, v223, v214
	s_waitcnt lgkmcnt(2)
	v_mfma_f32_32x32x16_bf16 v[96:111], v[228:231], v[116:119], v[96:111]
	v_add_f32_e32 v199, v199, v207
	v_add_f32_e32 v226, v223, v208
	v_cvt_pk_bf16_f32 v234, v211, v215
	ds_read_b128 v[222:225], v222 offset:8192
	v_add_f32_e32 v199, v199, v205
	v_add_f32_e32 v211, v226, v206
	v_cvt_pk_bf16_f32 v235, v209, v213
	v_add_f32_e32 v199, v199, v204
	v_add_f32_e32 v211, v211, v203
	s_waitcnt lgkmcnt(2)
	v_mfma_f32_32x32x16_bf16 v[80:95], v[236:239], v[116:119], v[80:95]
	v_add_u32_e32 v209, s34, v202
	ds_read_b128 v[226:229], v209
	v_add_f32_e32 v199, v199, v130
	v_add_f32_e32 v211, v211, v187
	s_waitcnt lgkmcnt(2)
	v_mfma_f32_32x32x16_bf16 v[96:111], v[216:219], v[120:123], v[96:111]
	v_add_f32_e32 v199, v199, v183
	v_add_f32_e32 v211, v211, v190
	v_cvt_pk_bf16_f32 v236, v210, v214
	ds_read_b128 v[240:243], v209 offset:8192
	v_add_f32_e32 v199, v199, v184
	v_add_f32_e32 v209, v211, v192
	v_cvt_pk_bf16_f32 v237, v207, v208
	v_add_f32_e32 v199, v199, v185
	v_add_f32_e32 v213, v209, v193
	s_waitcnt lgkmcnt(2)
	v_mfma_f32_32x32x16_bf16 v[80:95], v[222:225], v[120:123], v[80:95]
	s_add_i32 s36, s35, 0
	v_add_u32_e32 v214, s36, v178
	ds_read_b128 v[208:211], v214 offset:16384
	v_add_f32_e32 v199, v199, v188
	v_add_f32_e32 v207, v213, v196
	s_waitcnt lgkmcnt(2)
	v_mfma_f32_32x32x16_bf16 v[96:111], v[226:229], v[124:127], v[96:111]
	v_add_f32_e32 v199, v199, v191
	v_add_f32_e32 v207, v207, v197
	v_cvt_pk_bf16_f32 v238, v205, v206
	ds_read_b128 v[224:227], v214 offset:20480
	v_add_f32_e32 v199, v199, v189
	v_add_f32_e32 v205, v207, v194
	v_cvt_pk_bf16_f32 v239, v204, v203
	v_add_f32_e32 v216, v199, v186
	v_add_f32_e32 v199, v205, v195
	s_waitcnt lgkmcnt(2)
	v_mfma_f32_32x32x16_bf16 v[80:95], v[240:243], v[124:127], v[80:95]
	s_waitcnt lgkmcnt(1)
	v_mfma_f32_32x32x16_bf16 v[64:79], v[208:211], v[232:235], v[64:79]
	ds_read_b128 v[204:207], v214 offset:24576
	s_nop 5
	v_exp_f32_e32 v217, v96
	v_exp_f32_e32 v219, v97
	v_cvt_pk_bf16_f32 v228, v130, v187
	s_waitcnt lgkmcnt(1)
	v_mfma_f32_32x32x16_bf16 v[48:63], v[224:227], v[232:235], v[48:63]
	ds_read_b128 v[240:243], v214 offset:28672
	v_exp_f32_e32 v218, v98
	v_exp_f32_e32 v222, v99
	v_cvt_pk_bf16_f32 v229, v183, v190
	s_waitcnt lgkmcnt(1)
	v_mfma_f32_32x32x16_bf16 v[32:47], v[204:207], v[232:235], v[32:47]
	v_add_u32_e32 v130, s36, v179
	ds_read_b128 v[96:99], v130 offset:16384
	v_exp_f32_e32 v211, v100
	v_exp_f32_e32 v215, v101
	v_cvt_pk_bf16_f32 v230, v184, v192
	s_waitcnt lgkmcnt(1)
	v_mfma_f32_32x32x16_bf16 v[16:31], v[240:243], v[232:235], v[16:31]
	ds_read_b128 v[224:227], v130 offset:20480
	v_exp_f32_e32 v209, v102
	v_exp_f32_e32 v213, v103
	v_cvt_pk_bf16_f32 v231, v185, v193
	s_waitcnt lgkmcnt(1)
	v_mfma_f32_32x32x16_bf16 v[64:79], v[96:99], v[236:239], v[64:79]
	ds_read_b128 v[100:103], v130 offset:24576
	v_exp_f32_e32 v210, v104
	v_exp_f32_e32 v214, v105
	v_cvt_pk_bf16_f32 v232, v188, v196
	s_waitcnt lgkmcnt(1)
	v_mfma_f32_32x32x16_bf16 v[48:63], v[224:227], v[236:239], v[48:63]
	ds_read_b128 v[96:99], v130 offset:28672
	v_exp_f32_e32 v207, v106
	v_exp_f32_e32 v208, v107
	v_cvt_pk_bf16_f32 v233, v191, v197
	s_waitcnt lgkmcnt(1)
	v_mfma_f32_32x32x16_bf16 v[32:47], v[100:103], v[236:239], v[32:47]
	v_add_u32_e32 v183, s36, v180
	ds_read_b128 v[104:107], v183 offset:16384
	v_exp_f32_e32 v205, v108
	v_exp_f32_e32 v206, v109
	v_cvt_pk_bf16_f32 v234, v189, v194
	s_waitcnt lgkmcnt(1)
	v_mfma_f32_32x32x16_bf16 v[16:31], v[96:99], v[236:239], v[16:31]
	ds_read_b128 v[100:103], v183 offset:20480
	v_exp_f32_e32 v204, v110
	v_exp_f32_e32 v203, v111
	v_cvt_pk_bf16_f32 v235, v186, v195
	s_waitcnt lgkmcnt(1)
	v_mfma_f32_32x32x16_bf16 v[64:79], v[104:107], v[228:231], v[64:79]
	ds_read_b128 v[96:99], v183 offset:24576
	v_exp_f32_e32 v130, v80
	v_exp_f32_e32 v187, v81
	s_waitcnt lgkmcnt(1)
	v_mfma_f32_32x32x16_bf16 v[48:63], v[100:103], v[228:231], v[48:63]
	ds_read_b128 v[104:107], v183 offset:28672
	v_exp_f32_e32 v183, v82
	v_exp_f32_e32 v190, v83
	s_waitcnt lgkmcnt(1)
	v_mfma_f32_32x32x16_bf16 v[32:47], v[96:99], v[228:231], v[32:47]
	v_add_u32_e32 v100, s36, v181
	ds_read_b128 v[80:83], v100 offset:16384
	v_exp_f32_e32 v184, v84
	v_exp_f32_e32 v192, v85
	s_waitcnt lgkmcnt(1)
	v_mfma_f32_32x32x16_bf16 v[16:31], v[104:107], v[228:231], v[16:31]
	ds_read_b128 v[96:99], v100 offset:20480
	v_exp_f32_e32 v185, v86
	v_exp_f32_e32 v193, v87
	s_waitcnt lgkmcnt(1)
	v_mfma_f32_32x32x16_bf16 v[64:79], v[80:83], v[232:235], v[64:79]
	ds_read_b128 v[84:87], v100 offset:24576
	v_exp_f32_e32 v188, v88
	v_exp_f32_e32 v196, v89
	s_waitcnt lgkmcnt(1)
	v_mfma_f32_32x32x16_bf16 v[48:63], v[96:99], v[232:235], v[48:63]
	ds_read_b128 v[80:83], v100 offset:28672
	v_exp_f32_e32 v191, v90
	v_exp_f32_e32 v197, v91
	s_waitcnt lgkmcnt(1)
	v_mfma_f32_32x32x16_bf16 v[32:47], v[84:87], v[232:235], v[32:47]
	v_exp_f32_e32 v189, v92
	v_exp_f32_e32 v194, v93
	s_waitcnt lgkmcnt(0)
	v_mfma_f32_32x32x16_bf16 v[16:31], v[80:83], v[232:235], v[16:31]
	v_exp_f32_e32 v186, v94
	v_exp_f32_e32 v195, v95
	s_waitcnt vmcnt(0) lgkmcnt(0)
	s_add_i32 s33, s33, 1
	s_cmpk_eq_i32 s33, 0x84
	s_mov_b32 s36, s30
	s_mov_b32 s30, s31
	s_mov_b32 s31, s35
	s_barrier
	s_cbranch_scc1 .LBB0_834
